# speedup vs baseline: 1.0100x; 1.0027x over previous
; #define WAIT_V(n) asm volatile("s_waitcnt vmcnt(" #n ")" ::: "memory")
; #define BAR __builtin_amdgcn_s_barrier()
;     ...
;     STAGE(SB(0, 0), Bt, bcol, 0); STAGE(SA(0, 0), A, brow, 0);
;     STAGE(SB(0, 1), Bt, bcol + HALF, 0); STAGE(SA(0, 1), A, brow + HALF, 0);
;     if (wr == 1) BAR;
;     WAIT_V(4); BAR;
;     STAGE(SB(1, 0), Bt, bcol, 1); STAGE(SA(1, 0), A, brow, 1); STAGE(SB(1, 1), Bt, bcol + HALF, 1);
;     WAIT_V(6); BAR;
;     for (int t = 0; t < nt - 2; t += 2) {
.LBB0_97:
	s_or_b32 s34, s48, 1
	s_mov_b32 s35, s49
	s_lshl_b64 s[42:43], s[34:35], 6
	s_add_u32 s34, s42, s6
	s_addc_u32 s35, s43, s4
	s_lshl_b64 s[34:35], s[34:35], 1
	s_add_u32 s44, s24, s34
	s_addc_u32 s45, s25, s35
	s_add_i32 s34, s15, 0x18000
	s_add_i32 s35, s15, 0x1a000
	s_add_u32 s4, s42, s5
	s_addc_u32 s5, s43, s7
	s_lshl_b64 s[4:5], s[4:5], 1
	v_mov_b32_e32 v141, v1
	s_waitcnt vmcnt(4)
	s_barrier
	s_mov_b32 m0, s34
	v_lshl_add_u64 v[4:5], s[44:45], 0, v[0:1]
	s_add_u32 s4, s22, s4
	global_load_lds_dwordx4 v[4:5], off
	v_lshl_add_u64 v[4:5], s[44:45], 0, v[140:141]
	s_mov_b32 m0, s35
	s_addc_u32 s5, s23, s5
	s_add_i32 s37, s15, 0x8000
	global_load_lds_dwordx4 v[4:5], off
	s_mov_b32 m0, s37
	v_lshl_add_u64 v[4:5], s[4:5], 0, v[0:1]
	s_waitcnt lgkmcnt(0)
	s_add_i32 s38, s15, 0xa000
	global_load_lds_dwordx4 v[4:5], off
	v_lshl_add_u64 v[4:5], s[4:5], 0, v[140:141]
	s_add_u32 s4, s42, s39
	s_addc_u32 s5, s43, s40
	s_lshl_b64 s[4:5], s[4:5], 1
	s_add_u32 s4, s24, s4
	s_mov_b32 m0, s38
	s_addc_u32 s5, s25, s5
	s_add_i32 s41, s15, 0x1c000
	global_load_lds_dwordx4 v[4:5], off
	s_mov_b32 m0, s41
	v_lshl_add_u64 v[4:5], s[4:5], 0, v[0:1]
	s_add_i32 s42, s15, 0x1e000
	global_load_lds_dwordx4 v[4:5], off
	v_lshl_add_u64 v[4:5], s[4:5], 0, v[140:141]
	s_mov_b32 m0, s42
	v_and_b32_e32 v3, 15, v2
	global_load_lds_dwordx4 v[4:5], off
	v_and_b32_e32 v6, 48, v2
	v_lshlrev_b32_e32 v2, 2, v2
	v_lshlrev_b32_e32 v4, 6, v3
	v_and_b32_e32 v2, 32, v2
	v_bitop3_b32 v142, v4, v2, v6 bitop3:0x36
	v_or_b32_e32 v2, s33, v3
	v_lshlrev_b32_e32 v4, 6, v2
	v_lshlrev_b32_e32 v2, 2, v2
	v_and_b32_e32 v4, 0x3c0, v4
	v_and_b32_e32 v2, 32, v2
	v_readlane_b32 s4, v245, 36
	s_add_i32 s43, s14, -2
	s_mul_i32 s40, s29, 0x2c00
	v_bitop3_b32 v4, v4, v2, v6 bitop3:0x36
	v_or_b32_e32 v2, s4, v3
	s_mul_hi_i32 s39, s29, 0x2c00
	s_add_u32 s55, s22, s40
	v_lshlrev_b32_e32 v5, 6, v2
	v_lshlrev_b32_e32 v2, 2, v2
	s_addc_u32 s57, s23, s39
	v_and_b32_e32 v5, 0x3c0, v5
	v_and_b32_e32 v2, 32, v2
	v_readlane_b32 s4, v245, 37
	s_ashr_i32 s7, s6, 31
	v_bitop3_b32 v5, v5, v2, v6 bitop3:0x36
	v_or_b32_e32 v2, s4, v3
	s_lshl_b64 s[4:5], s[48:49], 7
	s_lshl_b64 s[6:7], s[6:7], 1
	s_add_u32 s6, s24, s6
	v_lshlrev_b32_e32 v7, 6, v2
	v_lshlrev_b32_e32 v2, 2, v2
	s_addc_u32 s7, s25, s7
	s_mul_i32 s44, s20, 0x2c00
	v_and_b32_e32 v7, 0x3c0, v7
	v_and_b32_e32 v2, 32, v2
	s_mul_hi_i32 s45, s20, 0x2c00
	s_add_u32 s44, s22, s44
	v_bitop3_b32 v7, v7, v2, v6 bitop3:0x36
	v_or_b32_e32 v2, s85, v3
	s_addc_u32 s45, s23, s45
	s_mul_i32 s50, s10, 0x2c00
	v_readlane_b32 s59, v244, 19
	v_lshlrev_b32_e32 v3, 6, v2
	v_lshlrev_b32_e32 v2, 2, v2
	s_mul_hi_i32 s51, s10, 0x2c00
	s_add_u32 s50, s24, s50
	v_add_u32_e32 v133, s59, v4
	v_readlane_b32 s59, v244, 20
	s_waitcnt vmcnt(6)
	v_and_b32_e32 v3, 0x3c0, v3
	v_and_b32_e32 v2, 32, v2
	s_addc_u32 s51, s25, s51
	v_add_u32_e32 v134, s59, v5
	v_readlane_b32 s59, v244, 21
	v_bitop3_b32 v3, v3, v2, v6 bitop3:0x36
	s_add_u32 s55, s55, 0x80
	v_mov_b32_e32 v2, 0
	v_add_u32_e32 v137, s59, v7
	v_readlane_b32 s59, v244, 22
	s_addc_u32 s57, s57, 0
	s_mov_b32 s58, 0
	v_add_u32_e32 v139, s59, v3
	v_mov_b32_e32 v3, v2
	v_mov_b32_e32 v4, v2
	v_mov_b32_e32 v5, v2
	v_mov_b32_e32 v6, v2
	v_mov_b32_e32 v7, v2
	v_mov_b32_e32 v8, v2
	v_mov_b32_e32 v9, v2
	v_mov_b32_e32 v10, v2
	v_mov_b32_e32 v11, v2
	v_mov_b32_e32 v12, v2
	v_mov_b32_e32 v13, v2
	v_mov_b32_e32 v14, v2
	v_mov_b32_e32 v15, v2
	v_mov_b32_e32 v16, v2
	v_mov_b32_e32 v17, v2
	v_mov_b32_e32 v18, v2
	v_mov_b32_e32 v19, v2
	v_mov_b32_e32 v20, v2
	v_mov_b32_e32 v21, v2
	v_mov_b32_e32 v22, v2
	v_mov_b32_e32 v23, v2
	v_mov_b32_e32 v24, v2
	v_mov_b32_e32 v25, v2
	v_mov_b32_e32 v26, v2
	v_mov_b32_e32 v27, v2
	v_mov_b32_e32 v28, v2
	v_mov_b32_e32 v29, v2
	v_mov_b32_e32 v30, v2
	v_mov_b32_e32 v31, v2
	v_mov_b32_e32 v32, v2
	v_mov_b32_e32 v33, v2
	v_mov_b32_e32 v34, v2
	v_mov_b32_e32 v35, v2
	v_mov_b32_e32 v36, v2
	v_mov_b32_e32 v37, v2
	v_mov_b32_e32 v38, v2
	v_mov_b32_e32 v39, v2
	v_mov_b32_e32 v40, v2
	v_mov_b32_e32 v41, v2
	v_mov_b32_e32 v42, v2
	v_mov_b32_e32 v43, v2
	v_mov_b32_e32 v44, v2
	v_mov_b32_e32 v45, v2
	v_mov_b32_e32 v46, v2
	v_mov_b32_e32 v47, v2
	v_mov_b32_e32 v48, v2
	v_mov_b32_e32 v49, v2
	v_mov_b32_e32 v50, v2
	v_mov_b32_e32 v51, v2
	v_mov_b32_e32 v52, v2
	v_mov_b32_e32 v53, v2
	v_mov_b32_e32 v54, v2
	v_mov_b32_e32 v55, v2
	v_mov_b32_e32 v56, v2
	v_mov_b32_e32 v57, v2
	v_mov_b32_e32 v58, v2
	v_mov_b32_e32 v59, v2
	v_mov_b32_e32 v60, v2
	v_mov_b32_e32 v61, v2
	v_mov_b32_e32 v62, v2
	v_mov_b32_e32 v63, v2
	v_mov_b32_e32 v64, v2
	v_mov_b32_e32 v65, v2
	v_mov_b32_e32 v66, v2
	v_mov_b32_e32 v67, v2
	v_mov_b32_e32 v68, v2
	v_mov_b32_e32 v69, v2
	v_mov_b32_e32 v70, v2
	v_mov_b32_e32 v71, v2
	v_mov_b32_e32 v72, v2
	v_mov_b32_e32 v73, v2
	v_mov_b32_e32 v74, v2
	v_mov_b32_e32 v75, v2
	v_mov_b32_e32 v76, v2
	v_mov_b32_e32 v77, v2
	v_mov_b32_e32 v78, v2
	v_mov_b32_e32 v79, v2
	v_mov_b32_e32 v80, v2
	v_mov_b32_e32 v81, v2
	v_mov_b32_e32 v82, v2
	v_mov_b32_e32 v83, v2
	v_mov_b32_e32 v84, v2
	v_mov_b32_e32 v85, v2
	v_mov_b32_e32 v86, v2
	v_mov_b32_e32 v87, v2
	v_mov_b32_e32 v88, v2
	v_mov_b32_e32 v89, v2
	v_mov_b32_e32 v90, v2
	v_mov_b32_e32 v91, v2
	v_mov_b32_e32 v92, v2
	v_mov_b32_e32 v93, v2
	v_mov_b32_e32 v94, v2
	v_mov_b32_e32 v95, v2
	v_mov_b32_e32 v96, v2
	v_mov_b32_e32 v97, v2
	v_mov_b32_e32 v98, v2
	v_mov_b32_e32 v99, v2
	v_mov_b32_e32 v100, v2
	v_mov_b32_e32 v101, v2
	v_mov_b32_e32 v102, v2
	v_mov_b32_e32 v103, v2
	v_mov_b32_e32 v104, v2
	v_mov_b32_e32 v105, v2
	v_mov_b32_e32 v106, v2
	v_mov_b32_e32 v107, v2
	v_mov_b32_e32 v108, v2
	v_mov_b32_e32 v109, v2
	v_mov_b32_e32 v110, v2
	v_mov_b32_e32 v111, v2
	v_mov_b32_e32 v112, v2
	v_mov_b32_e32 v113, v2
	v_mov_b32_e32 v114, v2
	v_mov_b32_e32 v115, v2
	v_mov_b32_e32 v116, v2
	v_mov_b32_e32 v117, v2
	v_mov_b32_e32 v118, v2
	v_mov_b32_e32 v119, v2
	v_mov_b32_e32 v120, v2
	v_mov_b32_e32 v121, v2
	v_mov_b32_e32 v122, v2
	v_mov_b32_e32 v123, v2
	v_mov_b32_e32 v124, v2
	v_mov_b32_e32 v125, v2
	v_mov_b32_e32 v126, v2
	v_mov_b32_e32 v127, v2
	v_mov_b32_e32 v128, v2
	v_mov_b32_e32 v129, v2
	v_readlane_b32 vcc_lo, v245, 30
	s_nop 0
	s_cmpk_lt_u32 vcc_lo, 0x1000
	s_cbranch_scc0 .Lgp_98
	s_setprio 1

; #define WAIT_V(n) asm volatile("s_waitcnt vmcnt(" #n ")" ::: "memory")
; #define BAR __builtin_amdgcn_s_barrier()
;     ...
;     STAGE(SB(0, 0), Bt, bcol, 0); STAGE(SA(0, 0), A, brow, 0);
;     STAGE(SB(0, 1), Bt, bcol + HALF, 0); STAGE(SA(0, 1), A, brow + HALF, 0);
;     if (wr == 1) BAR;
;     WAIT_V(4); BAR;
;     STAGE(SB(1, 0), Bt, bcol, 1); STAGE(SA(1, 0), A, brow, 1); STAGE(SB(1, 1), Bt, bcol + HALF, 1);
;     WAIT_V(6); BAR;
;     for (int t = 0; t < nt - 2; t += 2) {
.LBB0_154:
	s_add_u32 s34, s12, 0x80
	s_addc_u32 s35, s13, 0
	s_add_i32 s12, s24, 0x18000
	v_mov_b32_e32 v141, v1
	s_waitcnt vmcnt(4)
	s_barrier
	s_mov_b32 m0, s12
	v_lshl_add_u64 v[4:5], s[34:35], 0, v[0:1]
	s_add_i32 s13, s24, 0x1a000
	global_load_lds_dwordx4 v[4:5], off
	v_lshl_add_u64 v[4:5], s[34:35], 0, v[140:141]
	s_add_u32 s34, s14, 0x80
	s_mov_b32 m0, s13
	s_addc_u32 s35, s15, 0
	s_add_i32 s14, s24, 0x8000
	global_load_lds_dwordx4 v[4:5], off
	s_mov_b32 m0, s14
	v_lshl_add_u64 v[4:5], s[34:35], 0, v[0:1]
	s_add_i32 s15, s24, 0xa000
	global_load_lds_dwordx4 v[4:5], off
	v_lshl_add_u64 v[4:5], s[34:35], 0, v[140:141]
	s_add_u32 s34, s16, 0x80
	s_mov_b32 m0, s15
	s_addc_u32 s35, s17, 0
	s_add_i32 s16, s24, 0x1c000
	global_load_lds_dwordx4 v[4:5], off
	s_mov_b32 m0, s16
	v_lshl_add_u64 v[4:5], s[34:35], 0, v[0:1]
	s_add_i32 s17, s24, 0x1e000
	global_load_lds_dwordx4 v[4:5], off
	v_lshl_add_u64 v[4:5], s[34:35], 0, v[140:141]
	s_mov_b32 m0, s17
	v_and_b32_e32 v3, 15, v2
	global_load_lds_dwordx4 v[4:5], off
	v_and_b32_e32 v6, 48, v2
	v_lshlrev_b32_e32 v2, 2, v2
	v_lshlrev_b32_e32 v4, 6, v3
	v_and_b32_e32 v2, 32, v2
	v_bitop3_b32 v142, v4, v2, v6 bitop3:0x36
	v_or_b32_e32 v2, s33, v3
	v_lshlrev_b32_e32 v4, 6, v2
	v_lshlrev_b32_e32 v2, 2, v2
	v_and_b32_e32 v4, 0x3c0, v4
	v_and_b32_e32 v2, 32, v2
	v_readlane_b32 s34, v245, 36
	v_bitop3_b32 v4, v4, v2, v6 bitop3:0x36
	s_lshl_b32 s30, s30, 11
	v_or_b32_e32 v2, s34, v3
	v_lshlrev_b32_e32 v5, 6, v2
	v_lshlrev_b32_e32 v2, 2, v2
	v_and_b32_e32 v5, 0x3c0, v5
	v_and_b32_e32 v2, 32, v2
	v_readlane_b32 s34, v245, 37
	v_bitop3_b32 v5, v5, v2, v6 bitop3:0x36
	s_lshl_b32 s31, s31, 8
	v_or_b32_e32 v2, s34, v3
	v_lshlrev_b32_e32 v7, 6, v2
	v_lshlrev_b32_e32 v2, 2, v2
	s_add_i32 s30, s30, s31
	v_and_b32_e32 v7, 0x3c0, v7
	v_and_b32_e32 v2, 32, v2
	s_ashr_i32 s31, s30, 31
	v_bitop3_b32 v7, v7, v2, v6 bitop3:0x36
	v_or_b32_e32 v2, s85, v3
	s_lshl_b64 s[30:31], s[30:31], 12
	s_waitcnt lgkmcnt(0)
	v_readlane_b32 s38, v244, 19
	v_lshlrev_b32_e32 v3, 6, v2
	v_lshlrev_b32_e32 v2, 2, v2
	s_add_u32 s30, s74, s30
	v_add_u32_e32 v133, s38, v4
	v_readlane_b32 s38, v244, 20
	s_waitcnt vmcnt(6)
	v_and_b32_e32 v3, 0x3c0, v3
	v_and_b32_e32 v2, 32, v2
	s_addc_u32 s31, s75, s31
	v_add_u32_e32 v134, s38, v5
	v_readlane_b32 s38, v244, 21
	v_bitop3_b32 v3, v3, v2, v6 bitop3:0x36
	s_add_u32 s34, s18, s10
	v_mov_b32_e32 v2, 0
	v_add_u32_e32 v137, s38, v7
	v_readlane_b32 s38, v244, 22
	s_addc_u32 s35, s19, s11
	s_mov_b32 s37, -2
	s_mov_b64 s[10:11], 0
	v_add_u32_e32 v139, s38, v3
	v_mov_b32_e32 v3, v2
	v_mov_b32_e32 v4, v2
	v_mov_b32_e32 v5, v2
	v_mov_b32_e32 v6, v2
	v_mov_b32_e32 v7, v2
	v_mov_b32_e32 v8, v2
	v_mov_b32_e32 v9, v2
	v_mov_b32_e32 v10, v2
	v_mov_b32_e32 v11, v2
	v_mov_b32_e32 v12, v2
	v_mov_b32_e32 v13, v2
	v_mov_b32_e32 v14, v2
	v_mov_b32_e32 v15, v2
	v_mov_b32_e32 v16, v2
	v_mov_b32_e32 v17, v2
	v_mov_b32_e32 v18, v2
	v_mov_b32_e32 v19, v2
	v_mov_b32_e32 v20, v2
	v_mov_b32_e32 v21, v2
	v_mov_b32_e32 v22, v2
	v_mov_b32_e32 v23, v2
	v_mov_b32_e32 v24, v2
	v_mov_b32_e32 v25, v2
	v_mov_b32_e32 v26, v2
	v_mov_b32_e32 v27, v2
	v_mov_b32_e32 v28, v2
	v_mov_b32_e32 v29, v2
	v_mov_b32_e32 v30, v2
	v_mov_b32_e32 v31, v2
	v_mov_b32_e32 v32, v2
	v_mov_b32_e32 v33, v2
	v_mov_b32_e32 v34, v2
	v_mov_b32_e32 v35, v2
	v_mov_b32_e32 v36, v2
	v_mov_b32_e32 v37, v2
	v_mov_b32_e32 v38, v2
	v_mov_b32_e32 v39, v2
	v_mov_b32_e32 v40, v2
	v_mov_b32_e32 v41, v2
	v_mov_b32_e32 v42, v2
	v_mov_b32_e32 v43, v2
	v_mov_b32_e32 v44, v2
	v_mov_b32_e32 v45, v2
	v_mov_b32_e32 v46, v2
	v_mov_b32_e32 v47, v2
	v_mov_b32_e32 v48, v2
	v_mov_b32_e32 v49, v2
	v_mov_b32_e32 v50, v2
	v_mov_b32_e32 v51, v2
	v_mov_b32_e32 v52, v2
	v_mov_b32_e32 v53, v2
	v_mov_b32_e32 v54, v2
	v_mov_b32_e32 v55, v2
	v_mov_b32_e32 v56, v2
	v_mov_b32_e32 v57, v2
	v_mov_b32_e32 v58, v2
	v_mov_b32_e32 v59, v2
	v_mov_b32_e32 v60, v2
	v_mov_b32_e32 v61, v2
	v_mov_b32_e32 v62, v2
	v_mov_b32_e32 v63, v2
	v_mov_b32_e32 v64, v2
	v_mov_b32_e32 v65, v2
	v_mov_b32_e32 v66, v2
	v_mov_b32_e32 v67, v2
	v_mov_b32_e32 v68, v2
	v_mov_b32_e32 v69, v2
	v_mov_b32_e32 v70, v2
	v_mov_b32_e32 v71, v2
	v_mov_b32_e32 v72, v2
	v_mov_b32_e32 v73, v2
	v_mov_b32_e32 v74, v2
	v_mov_b32_e32 v75, v2
	v_mov_b32_e32 v76, v2
	v_mov_b32_e32 v77, v2
	v_mov_b32_e32 v78, v2
	v_mov_b32_e32 v79, v2
	v_mov_b32_e32 v80, v2
	v_mov_b32_e32 v81, v2
	v_mov_b32_e32 v82, v2
	v_mov_b32_e32 v83, v2
	v_mov_b32_e32 v84, v2
	v_mov_b32_e32 v85, v2
	v_mov_b32_e32 v86, v2
	v_mov_b32_e32 v87, v2
	v_mov_b32_e32 v88, v2
	v_mov_b32_e32 v89, v2
	v_mov_b32_e32 v90, v2
	v_mov_b32_e32 v91, v2
	v_mov_b32_e32 v92, v2
	v_mov_b32_e32 v93, v2
	v_mov_b32_e32 v94, v2
	v_mov_b32_e32 v95, v2
	v_mov_b32_e32 v96, v2
	v_mov_b32_e32 v97, v2
	v_mov_b32_e32 v98, v2
	v_mov_b32_e32 v99, v2
	v_mov_b32_e32 v100, v2
	v_mov_b32_e32 v101, v2
	v_mov_b32_e32 v102, v2
	v_mov_b32_e32 v103, v2
	v_mov_b32_e32 v104, v2
	v_mov_b32_e32 v105, v2
	v_mov_b32_e32 v106, v2
	v_mov_b32_e32 v107, v2
	v_mov_b32_e32 v108, v2
	v_mov_b32_e32 v109, v2
	v_mov_b32_e32 v110, v2
	v_mov_b32_e32 v111, v2
	v_mov_b32_e32 v112, v2
	v_mov_b32_e32 v113, v2
	v_mov_b32_e32 v114, v2
	v_mov_b32_e32 v115, v2
	v_mov_b32_e32 v116, v2
	v_mov_b32_e32 v117, v2
	v_mov_b32_e32 v118, v2
	v_mov_b32_e32 v119, v2
	v_mov_b32_e32 v120, v2
	v_mov_b32_e32 v121, v2
	v_mov_b32_e32 v122, v2
	v_mov_b32_e32 v123, v2
	v_mov_b32_e32 v124, v2
	v_mov_b32_e32 v125, v2
	v_mov_b32_e32 v126, v2
	v_mov_b32_e32 v127, v2
	v_mov_b32_e32 v128, v2
	v_mov_b32_e32 v129, v2
	v_readlane_b32 vcc_lo, v245, 30
	s_nop 0
	s_cmpk_lt_u32 vcc_lo, 0x1000
	s_cbranch_scc0 .Lgp_155
	s_setprio 1

; #define WAIT_V(n) asm volatile("s_waitcnt vmcnt(" #n ")" ::: "memory")
; #define BAR __builtin_amdgcn_s_barrier()
;     ...
;     STAGE(SB(0, 0), Bt, bcol, 0); STAGE(SA(0, 0), A, brow, 0);
;     STAGE(SB(0, 1), Bt, bcol + HALF, 0); STAGE(SA(0, 1), A, brow + HALF, 0);
;     if (wr == 1) BAR;
;     WAIT_V(4); BAR;
;     STAGE(SB(1, 0), Bt, bcol, 1); STAGE(SA(1, 0), A, brow, 1); STAGE(SB(1, 1), Bt, bcol + HALF, 1);
;     WAIT_V(6); BAR;
;     for (int t = 0; t < nt - 2; t += 2) {
.LBB0_201:
	s_or_b32 s40, s48, 1
	s_mov_b32 s41, s49
	s_lshl_b64 s[44:45], s[40:41], 6
	s_add_u32 s4, s44, s4
	s_addc_u32 s5, s45, s5
	s_lshl_b64 s[4:5], s[4:5], 1
	s_add_u32 s4, s22, s4
	s_addc_u32 s5, s23, s5
	s_add_i32 s39, s21, 0x18000
	v_mov_b32_e32 v141, v1
	s_waitcnt vmcnt(4)
	s_barrier
	s_mov_b32 m0, s39
	v_lshl_add_u64 v[4:5], s[4:5], 0, v[0:1]
	s_add_i32 s40, s21, 0x1a000
	global_load_lds_dwordx4 v[4:5], off
	v_lshl_add_u64 v[4:5], s[4:5], 0, v[140:141]
	s_add_u32 s4, s44, s16
	s_addc_u32 s5, s45, s17
	s_lshl_b64 s[4:5], s[4:5], 1
	s_add_u32 s4, s74, s4
	s_mov_b32 m0, s40
	s_addc_u32 s5, s75, s5
	s_add_i32 s41, s21, 0x8000
	global_load_lds_dwordx4 v[4:5], off
	s_mov_b32 m0, s41
	v_lshl_add_u64 v[4:5], s[4:5], 0, v[0:1]
	s_add_i32 s42, s21, 0xa000
	global_load_lds_dwordx4 v[4:5], off
	v_lshl_add_u64 v[4:5], s[4:5], 0, v[140:141]
	s_add_u32 s4, s44, s18
	s_addc_u32 s5, s45, s19
	s_lshl_b64 s[4:5], s[4:5], 1
	s_add_u32 s4, s22, s4
	s_mov_b32 m0, s42
	s_addc_u32 s5, s23, s5
	s_add_i32 s18, s21, 0x1c000
	global_load_lds_dwordx4 v[4:5], off
	s_mov_b32 m0, s18
	v_lshl_add_u64 v[4:5], s[4:5], 0, v[0:1]
	s_add_i32 s19, s21, 0x1e000
	global_load_lds_dwordx4 v[4:5], off
	v_lshl_add_u64 v[4:5], s[4:5], 0, v[140:141]
	s_mov_b32 m0, s19
	v_and_b32_e32 v3, 15, v2
	global_load_lds_dwordx4 v[4:5], off
	v_and_b32_e32 v6, 48, v2
	v_lshlrev_b32_e32 v2, 2, v2
	v_lshlrev_b32_e32 v4, 6, v3
	v_and_b32_e32 v2, 32, v2
	v_bitop3_b32 v142, v4, v2, v6 bitop3:0x36
	v_or_b32_e32 v2, s33, v3
	v_lshlrev_b32_e32 v4, 6, v2
	v_lshlrev_b32_e32 v2, 2, v2
	s_lshl_b64 s[4:5], s[10:11], 12
	v_and_b32_e32 v4, 0x3c0, v4
	v_and_b32_e32 v2, 32, v2
	v_readlane_b32 s11, v245, 36
	s_add_i32 s43, s20, -2
	v_bitop3_b32 v4, v4, v2, v6 bitop3:0x36
	v_or_b32_e32 v2, s11, v3
	s_add_u32 s55, s74, s4
	v_lshlrev_b32_e32 v5, 6, v2
	v_lshlrev_b32_e32 v2, 2, v2
	s_addc_u32 s57, s75, s5
	v_and_b32_e32 v5, 0x3c0, v5
	v_and_b32_e32 v2, 32, v2
	v_readlane_b32 s11, v245, 37
	s_lshl_b64 s[16:17], s[48:49], 7
	s_lshl_b64 s[44:45], s[14:15], 12
	v_bitop3_b32 v5, v5, v2, v6 bitop3:0x36
	v_or_b32_e32 v2, s11, v3
	s_add_u32 s11, s22, s44
	s_addc_u32 s44, s23, s45
	s_lshl_b64 s[50:51], s[12:13], 12
	s_add_u32 s13, s74, s50
	v_lshlrev_b32_e32 v7, 6, v2
	v_lshlrev_b32_e32 v2, 2, v2
	s_addc_u32 s45, s75, s51
	v_and_b32_e32 v7, 0x3c0, v7
	v_and_b32_e32 v2, 32, v2
	s_add_u32 s50, s55, 0x80
	v_bitop3_b32 v7, v7, v2, v6 bitop3:0x36
	v_or_b32_e32 v2, s85, v3
	s_addc_u32 s51, s57, 0
	v_readlane_b32 s57, v244, 19
	v_lshlrev_b32_e32 v3, 6, v2
	v_lshlrev_b32_e32 v2, 2, v2
	v_add_u32_e32 v133, s57, v4
	v_readlane_b32 s57, v244, 20
	s_waitcnt vmcnt(6)
	v_and_b32_e32 v3, 0x3c0, v3
	v_and_b32_e32 v2, 32, v2
	v_add_u32_e32 v134, s57, v5
	v_readlane_b32 s57, v244, 21
	v_bitop3_b32 v3, v3, v2, v6 bitop3:0x36
	v_mov_b32_e32 v2, 0
	v_add_u32_e32 v137, s57, v7
	v_readlane_b32 s57, v244, 22
	s_mov_b32 s55, 0
	v_mov_b32_e32 v4, v2
	v_add_u32_e32 v139, s57, v3
	v_mov_b32_e32 v3, v2
	v_mov_b32_e32 v5, v2
	v_mov_b32_e32 v6, v2
	v_mov_b32_e32 v7, v2
	v_mov_b32_e32 v8, v2
	v_mov_b32_e32 v9, v2
	v_mov_b32_e32 v10, v2
	v_mov_b32_e32 v11, v2
	v_mov_b32_e32 v12, v2
	v_mov_b32_e32 v13, v2
	v_mov_b32_e32 v14, v2
	v_mov_b32_e32 v15, v2
	v_mov_b32_e32 v16, v2
	v_mov_b32_e32 v17, v2
	v_mov_b32_e32 v18, v2
	v_mov_b32_e32 v19, v2
	v_mov_b32_e32 v20, v2
	v_mov_b32_e32 v21, v2
	v_mov_b32_e32 v22, v2
	v_mov_b32_e32 v23, v2
	v_mov_b32_e32 v24, v2
	v_mov_b32_e32 v25, v2
	v_mov_b32_e32 v26, v2
	v_mov_b32_e32 v27, v2
	v_mov_b32_e32 v28, v2
	v_mov_b32_e32 v29, v2
	v_mov_b32_e32 v30, v2
	v_mov_b32_e32 v31, v2
	v_mov_b32_e32 v32, v2
	v_mov_b32_e32 v33, v2
	v_mov_b32_e32 v34, v2
	v_mov_b32_e32 v35, v2
	v_mov_b32_e32 v36, v2
	v_mov_b32_e32 v37, v2
	v_mov_b32_e32 v38, v2
	v_mov_b32_e32 v39, v2
	v_mov_b32_e32 v40, v2
	v_mov_b32_e32 v41, v2
	v_mov_b32_e32 v42, v2
	v_mov_b32_e32 v43, v2
	v_mov_b32_e32 v44, v2
	v_mov_b32_e32 v45, v2
	v_mov_b32_e32 v46, v2
	v_mov_b32_e32 v47, v2
	v_mov_b32_e32 v48, v2
	v_mov_b32_e32 v49, v2
	v_mov_b32_e32 v50, v2
	v_mov_b32_e32 v51, v2
	v_mov_b32_e32 v52, v2
	v_mov_b32_e32 v53, v2
	v_mov_b32_e32 v54, v2
	v_mov_b32_e32 v55, v2
	v_mov_b32_e32 v56, v2
	v_mov_b32_e32 v57, v2
	v_mov_b32_e32 v58, v2
	v_mov_b32_e32 v59, v2
	v_mov_b32_e32 v60, v2
	v_mov_b32_e32 v61, v2
	v_mov_b32_e32 v62, v2
	v_mov_b32_e32 v63, v2
	v_mov_b32_e32 v64, v2
	v_mov_b32_e32 v65, v2
	v_mov_b32_e32 v66, v2
	v_mov_b32_e32 v67, v2
	v_mov_b32_e32 v68, v2
	v_mov_b32_e32 v69, v2
	v_mov_b32_e32 v70, v2
	v_mov_b32_e32 v71, v2
	v_mov_b32_e32 v72, v2
	v_mov_b32_e32 v73, v2
	v_mov_b32_e32 v74, v2
	v_mov_b32_e32 v75, v2
	v_mov_b32_e32 v76, v2
	v_mov_b32_e32 v77, v2
	v_mov_b32_e32 v78, v2
	v_mov_b32_e32 v79, v2
	v_mov_b32_e32 v80, v2
	v_mov_b32_e32 v81, v2
	v_mov_b32_e32 v82, v2
	v_mov_b32_e32 v83, v2
	v_mov_b32_e32 v84, v2
	v_mov_b32_e32 v85, v2
	v_mov_b32_e32 v86, v2
	v_mov_b32_e32 v87, v2
	v_mov_b32_e32 v88, v2
	v_mov_b32_e32 v89, v2
	v_mov_b32_e32 v90, v2
	v_mov_b32_e32 v91, v2
	v_mov_b32_e32 v92, v2
	v_mov_b32_e32 v93, v2
	v_mov_b32_e32 v94, v2
	v_mov_b32_e32 v95, v2
	v_mov_b32_e32 v96, v2
	v_mov_b32_e32 v97, v2
	v_mov_b32_e32 v98, v2
	v_mov_b32_e32 v99, v2
	v_mov_b32_e32 v100, v2
	v_mov_b32_e32 v101, v2
	v_mov_b32_e32 v102, v2
	v_mov_b32_e32 v103, v2
	v_mov_b32_e32 v104, v2
	v_mov_b32_e32 v105, v2
	v_mov_b32_e32 v106, v2
	v_mov_b32_e32 v107, v2
	v_mov_b32_e32 v108, v2
	v_mov_b32_e32 v109, v2
	v_mov_b32_e32 v110, v2
	v_mov_b32_e32 v111, v2
	v_mov_b32_e32 v112, v2
	v_mov_b32_e32 v113, v2
	v_mov_b32_e32 v114, v2
	v_mov_b32_e32 v115, v2
	v_mov_b32_e32 v116, v2
	v_mov_b32_e32 v117, v2
	v_mov_b32_e32 v118, v2
	v_mov_b32_e32 v119, v2
	v_mov_b32_e32 v120, v2
	v_mov_b32_e32 v121, v2
	v_mov_b32_e32 v122, v2
	v_mov_b32_e32 v123, v2
	v_mov_b32_e32 v124, v2
	v_mov_b32_e32 v125, v2
	v_mov_b32_e32 v126, v2
	v_mov_b32_e32 v127, v2
	v_mov_b32_e32 v128, v2
	v_mov_b32_e32 v129, v2
	v_readlane_b32 vcc_lo, v245, 30
	s_nop 0
	s_cmpk_lt_u32 vcc_lo, 0x1000
	s_cbranch_scc0 .Lgp_202
	s_setprio 1

; #define WAIT_V(n) asm volatile("s_waitcnt vmcnt(" #n ")" ::: "memory")
; #define BAR __builtin_amdgcn_s_barrier()
;     ...
;     STAGE(SB(0, 0), Bt, bcol, 0); STAGE(SA(0, 0), A, brow, 0);
;     STAGE(SB(0, 1), Bt, bcol + HALF, 0); STAGE(SA(0, 1), A, brow + HALF, 0);
;     if (wr == 1) BAR;
;     WAIT_V(4); BAR;
;     STAGE(SB(1, 0), Bt, bcol, 1); STAGE(SA(1, 0), A, brow, 1); STAGE(SB(1, 1), Bt, bcol + HALF, 1);
;     WAIT_V(6); BAR;
;     for (int t = 0; t < nt - 2; t += 2) {
.LBB0_417:
	s_add_u32 s34, s8, 0x80
	s_addc_u32 s35, s9, 0
	s_add_i32 s8, s15, 0x18000
	v_mov_b32_e32 v141, v1
	s_waitcnt vmcnt(4)
	s_barrier
	s_mov_b32 m0, s8
	v_lshl_add_u64 v[4:5], s[34:35], 0, v[0:1]
	s_add_i32 s9, s15, 0x1a000
	global_load_lds_dwordx4 v[4:5], off
	v_lshl_add_u64 v[4:5], s[34:35], 0, v[140:141]
	s_add_u32 s34, s18, 0x80
	s_mov_b32 m0, s9
	s_addc_u32 s35, s19, 0
	s_add_i32 s18, s15, 0x8000
	global_load_lds_dwordx4 v[4:5], off
	s_mov_b32 m0, s18
	v_lshl_add_u64 v[4:5], s[34:35], 0, v[0:1]
	s_add_i32 s19, s15, 0xa000
	global_load_lds_dwordx4 v[4:5], off
	v_lshl_add_u64 v[4:5], s[34:35], 0, v[140:141]
	s_add_u32 s34, s20, 0x80
	s_mov_b32 m0, s19
	s_addc_u32 s35, s21, 0
	s_add_i32 s20, s15, 0x1c000
	global_load_lds_dwordx4 v[4:5], off
	s_mov_b32 m0, s20
	v_lshl_add_u64 v[4:5], s[34:35], 0, v[0:1]
	s_add_i32 s21, s15, 0x1e000
	global_load_lds_dwordx4 v[4:5], off
	v_lshl_add_u64 v[4:5], s[34:35], 0, v[140:141]
	s_mov_b32 m0, s21
	v_and_b32_e32 v3, 15, v2
	global_load_lds_dwordx4 v[4:5], off
	v_and_b32_e32 v6, 48, v2
	v_lshlrev_b32_e32 v2, 2, v2
	v_lshlrev_b32_e32 v4, 6, v3
	v_and_b32_e32 v2, 32, v2
	v_bitop3_b32 v142, v4, v2, v6 bitop3:0x36
	v_or_b32_e32 v2, s33, v3
	v_lshlrev_b32_e32 v4, 6, v2
	v_lshlrev_b32_e32 v2, 2, v2
	v_and_b32_e32 v4, 0x3c0, v4
	v_and_b32_e32 v2, 32, v2
	v_readlane_b32 s34, v245, 36
	v_bitop3_b32 v4, v4, v2, v6 bitop3:0x36
	s_lshl_b32 s30, s30, 11
	v_or_b32_e32 v2, s34, v3
	v_lshlrev_b32_e32 v5, 6, v2
	v_lshlrev_b32_e32 v2, 2, v2
	v_and_b32_e32 v5, 0x3c0, v5
	v_and_b32_e32 v2, 32, v2
	v_readlane_b32 s34, v245, 37
	v_bitop3_b32 v5, v5, v2, v6 bitop3:0x36
	s_lshl_b32 s31, s31, 8
	v_or_b32_e32 v2, s34, v3
	v_lshlrev_b32_e32 v7, 6, v2
	v_lshlrev_b32_e32 v2, 2, v2
	s_add_i32 s30, s30, s31
	v_and_b32_e32 v7, 0x3c0, v7
	v_and_b32_e32 v2, 32, v2
	s_ashr_i32 s31, s30, 31
	v_bitop3_b32 v7, v7, v2, v6 bitop3:0x36
	v_or_b32_e32 v2, s85, v3
	s_lshl_b64 s[30:31], s[30:31], 12
	v_readlane_b32 s37, v244, 19
	v_lshlrev_b32_e32 v3, 6, v2
	v_lshlrev_b32_e32 v2, 2, v2
	s_add_u32 s30, s74, s30
	v_add_u32_e32 v133, s37, v4
	v_readlane_b32 s37, v244, 20
	s_waitcnt vmcnt(6)
	v_and_b32_e32 v3, 0x3c0, v3
	v_and_b32_e32 v2, 32, v2
	s_addc_u32 s31, s75, s31
	v_add_u32_e32 v134, s37, v5
	v_readlane_b32 s37, v244, 21
	v_bitop3_b32 v3, v3, v2, v6 bitop3:0x36
	s_add_u32 s34, s38, s6
	v_mov_b32_e32 v2, 0
	v_add_u32_e32 v137, s37, v7
	v_readlane_b32 s37, v244, 22
	s_addc_u32 s35, s39, s7
	s_mov_b32 s36, -2
	s_mov_b64 s[6:7], 0
	v_add_u32_e32 v139, s37, v3
	v_mov_b32_e32 v3, v2
	v_mov_b32_e32 v4, v2
	v_mov_b32_e32 v5, v2
	v_mov_b32_e32 v6, v2
	v_mov_b32_e32 v7, v2
	v_mov_b32_e32 v8, v2
	v_mov_b32_e32 v9, v2
	v_mov_b32_e32 v10, v2
	v_mov_b32_e32 v11, v2
	v_mov_b32_e32 v12, v2
	v_mov_b32_e32 v13, v2
	v_mov_b32_e32 v14, v2
	v_mov_b32_e32 v15, v2
	v_mov_b32_e32 v16, v2
	v_mov_b32_e32 v17, v2
	v_mov_b32_e32 v18, v2
	v_mov_b32_e32 v19, v2
	v_mov_b32_e32 v20, v2
	v_mov_b32_e32 v21, v2
	v_mov_b32_e32 v22, v2
	v_mov_b32_e32 v23, v2
	v_mov_b32_e32 v24, v2
	v_mov_b32_e32 v25, v2
	v_mov_b32_e32 v26, v2
	v_mov_b32_e32 v27, v2
	v_mov_b32_e32 v28, v2
	v_mov_b32_e32 v29, v2
	v_mov_b32_e32 v30, v2
	v_mov_b32_e32 v31, v2
	v_mov_b32_e32 v32, v2
	v_mov_b32_e32 v33, v2
	v_mov_b32_e32 v34, v2
	v_mov_b32_e32 v35, v2
	v_mov_b32_e32 v36, v2
	v_mov_b32_e32 v37, v2
	v_mov_b32_e32 v38, v2
	v_mov_b32_e32 v39, v2
	v_mov_b32_e32 v40, v2
	v_mov_b32_e32 v41, v2
	v_mov_b32_e32 v42, v2
	v_mov_b32_e32 v43, v2
	v_mov_b32_e32 v44, v2
	v_mov_b32_e32 v45, v2
	v_mov_b32_e32 v46, v2
	v_mov_b32_e32 v47, v2
	v_mov_b32_e32 v48, v2
	v_mov_b32_e32 v49, v2
	v_mov_b32_e32 v50, v2
	v_mov_b32_e32 v51, v2
	v_mov_b32_e32 v52, v2
	v_mov_b32_e32 v53, v2
	v_mov_b32_e32 v54, v2
	v_mov_b32_e32 v55, v2
	v_mov_b32_e32 v56, v2
	v_mov_b32_e32 v57, v2
	v_mov_b32_e32 v58, v2
	v_mov_b32_e32 v59, v2
	v_mov_b32_e32 v60, v2
	v_mov_b32_e32 v61, v2
	v_mov_b32_e32 v62, v2
	v_mov_b32_e32 v63, v2
	v_mov_b32_e32 v64, v2
	v_mov_b32_e32 v65, v2
	v_mov_b32_e32 v66, v2
	v_mov_b32_e32 v67, v2
	v_mov_b32_e32 v68, v2
	v_mov_b32_e32 v69, v2
	v_mov_b32_e32 v70, v2
	v_mov_b32_e32 v71, v2
	v_mov_b32_e32 v72, v2
	v_mov_b32_e32 v73, v2
	v_mov_b32_e32 v74, v2
	v_mov_b32_e32 v75, v2
	v_mov_b32_e32 v76, v2
	v_mov_b32_e32 v77, v2
	v_mov_b32_e32 v78, v2
	v_mov_b32_e32 v79, v2
	v_mov_b32_e32 v80, v2
	v_mov_b32_e32 v81, v2
	v_mov_b32_e32 v82, v2
	v_mov_b32_e32 v83, v2
	v_mov_b32_e32 v84, v2
	v_mov_b32_e32 v85, v2
	v_mov_b32_e32 v86, v2
	v_mov_b32_e32 v87, v2
	v_mov_b32_e32 v88, v2
	v_mov_b32_e32 v89, v2
	v_mov_b32_e32 v90, v2
	v_mov_b32_e32 v91, v2
	v_mov_b32_e32 v92, v2
	v_mov_b32_e32 v93, v2
	v_mov_b32_e32 v94, v2
	v_mov_b32_e32 v95, v2
	v_mov_b32_e32 v96, v2
	v_mov_b32_e32 v97, v2
	v_mov_b32_e32 v98, v2
	v_mov_b32_e32 v99, v2
	v_mov_b32_e32 v100, v2
	v_mov_b32_e32 v101, v2
	v_mov_b32_e32 v102, v2
	v_mov_b32_e32 v103, v2
	v_mov_b32_e32 v104, v2
	v_mov_b32_e32 v105, v2
	v_mov_b32_e32 v106, v2
	v_mov_b32_e32 v107, v2
	v_mov_b32_e32 v108, v2
	v_mov_b32_e32 v109, v2
	v_mov_b32_e32 v110, v2
	v_mov_b32_e32 v111, v2
	v_mov_b32_e32 v112, v2
	v_mov_b32_e32 v113, v2
	v_mov_b32_e32 v114, v2
	v_mov_b32_e32 v115, v2
	v_mov_b32_e32 v116, v2
	v_mov_b32_e32 v117, v2
	v_mov_b32_e32 v118, v2
	v_mov_b32_e32 v119, v2
	v_mov_b32_e32 v120, v2
	v_mov_b32_e32 v121, v2
	v_mov_b32_e32 v122, v2
	v_mov_b32_e32 v123, v2
	v_mov_b32_e32 v124, v2
	v_mov_b32_e32 v125, v2
	v_mov_b32_e32 v126, v2
	v_mov_b32_e32 v127, v2
	v_mov_b32_e32 v128, v2
	v_mov_b32_e32 v129, v2
	v_readlane_b32 vcc_lo, v245, 30
	s_nop 0
	s_cmpk_lt_u32 vcc_lo, 0x1000
	s_cbranch_scc0 .Lgp_418
	s_setprio 1
